# s20 + site2_cond_wb: Fourier image written through, barrier 2 skips the leader's L2 write-back when placement is verified
# speedup vs baseline: 1.0103x; 1.0009x over previous
.LBB0_349:
	s_cmp_gt_i32 s83, 3
	s_cselect_b64 s[0:1], -1, 0
	s_and_b64 s[4:5], s[18:19], s[0:1]
	s_andn2_b64 vcc, exec, s[4:5]
	s_cbranch_vccnz .LBB0_403
	s_waitcnt vmcnt(0)
	s_waitcnt vmcnt(0)
	s_barrier
	s_and_saveexec_b64 s[4:5], s[94:95]
	s_cbranch_execz .LBB0_402
	v_mov_b32_e32 v1, 0x23ff0
	ds_read_b32 v2, v1
	ds_read_b32 v3, v1 offset:4
	s_add_u32 s6, s80, 0x2380000
	s_addc_u32 s7, s81, 0
	s_lshl_b32 s8, s87, 8
	s_add_i32 s9, s8, 0x1400
	s_add_i32 s8, s8, 0x2400
	v_mov_b32_e32 v4, s9
	v_mov_b32_e32 v5, 1
	global_atomic_add v6, v4, v5, s[6:7] sc0
	buffer_inv sc1
	s_waitcnt vmcnt(0) lgkmcnt(0)
	v_readfirstlane_b32 s10, v6
	v_readfirstlane_b32 s11, v2
	v_readfirstlane_b32 s16, v3
	s_add_i32 s10, s10, 1
	s_mul_i32 s11, s11, 3
	s_cmp_lg_u32 s10, s11
	s_cbranch_scc1 .Lxb_nl_2
	v_readlane_b32 s9, v255, 63
	s_nop 0
	s_cmp_eq_u32 s9, 0
	s_cbranch_scc1 .Lxb_nowb_2
	buffer_wbl2 sc1
	s_waitcnt vmcnt(0)
.Lxb_nowb_2:
	v_mov_b32_e32 v4, 0x3400
	global_atomic_add v6, v4, v5, s[6:7] sc0
	s_waitcnt vmcnt(0)
	v_readfirstlane_b32 s10, v6
	s_add_i32 s10, s10, 1
	s_mul_i32 s16, s16, 3
	s_cmp_lg_u32 s10, s16
	s_cbranch_scc1 .Lxb_nl_2
	v_mov_b32_e32 v4, 0x2400
	global_atomic_add v4, v5, s[6:7]
	global_atomic_add v4, v5, s[6:7] offset:256
	global_atomic_add v4, v5, s[6:7] offset:512
	global_atomic_add v4, v5, s[6:7] offset:768
	global_atomic_add v4, v5, s[6:7] offset:1024
	global_atomic_add v4, v5, s[6:7] offset:1280
	global_atomic_add v4, v5, s[6:7] offset:1536
	global_atomic_add v4, v5, s[6:7] offset:1792
	global_atomic_add v4, v5, s[6:7] offset:2048
	global_atomic_add v4, v5, s[6:7] offset:2304
	global_atomic_add v4, v5, s[6:7] offset:2560
	global_atomic_add v4, v5, s[6:7] offset:2816
	global_atomic_add v4, v5, s[6:7] offset:3072
	global_atomic_add v4, v5, s[6:7] offset:3328
	global_atomic_add v4, v5, s[6:7] offset:3584
	global_atomic_add v4, v5, s[6:7] offset:3840
	s_branch .Lxb_done_2
